# static s_setprio 1 for waves 0-3 instead of waves 4-7 (flips deleted), comparison of the two halves
# speedup vs baseline: 1.0059x; 1.0059x over previous
; #define LAS __attribute__((address_space(3)))
; __global__ void __launch_bounds__(512, 2) mk_fwd(Args args) {
;     extern __shared__ __attribute__((aligned(16))) unsigned char lds_raw[];
;     Frame F;
;     F.lds = (LAS unsigned char*)lds_raw; F.tid = threadIdx.x; F.lane = F.tid & 63; F.wave = __builtin_amdgcn_readfirstlane(F.tid >> 6); F.G = gridDim.x;
_Z6mk_fwd4Args:
	v_readfirstlane_b32 s98, v0
	s_nop 3
	s_and_b32 s98, s98, 0x3ff
	s_lshr_b32 s98, s98, 6
	s_cmp_lt_u32 s98, 4
	s_cbranch_scc0 .Lprio_done
	s_setprio 1
